# norm loops: 64-lane sum via DPP quad_perm/row_mirror + v_permlane16/32_swap instead of six ds_bpermute round trips (same butterfly, bit-identical)
# speedup vs baseline: 1.0078x; 1.0078x over previous
.LBB0_79:
	global_load_dwordx4 v[62:65], v[50:51], off offset:-3072
	global_load_dwordx4 v[66:69], v[50:51], off offset:-2048
	global_load_dwordx4 v[84:87], v[50:51], off offset:-1024
	global_load_dwordx4 v[80:83], v[50:51], off
	v_readlane_b32 s12, v252, 0
	v_readlane_b32 s13, v252, 1
	v_readlane_b32 s14, v252, 2
	v_readlane_b32 s15, v252, 3
	s_add_i32 s0, s0, 1
	s_cmp_ge_i32 s0, s2
	s_waitcnt vmcnt(2)
	v_pk_mul_f32 v[34:35], v[64:65], v[64:65]
	v_pk_mul_f32 v[36:37], v[62:63], v[62:63]
	s_nop 0
	v_pk_mov_b32 v[38:39], v[36:37], v[34:35] op_sel:[1,0]
	v_mov_b32_e32 v37, v35
	v_pk_add_f32 v[70:71], v[38:39], v[36:37]
	v_pk_mul_f32 v[34:35], v[68:69], v[68:69]
	v_pk_mul_f32 v[36:37], v[66:67], v[66:67]
	v_pk_add_f32 v[70:71], v[70:71], v[70:71] op_sel:[0,1] op_sel_hi:[1,0]
	v_pk_mov_b32 v[38:39], v[36:37], v[34:35] op_sel:[1,0]
	v_mov_b32_e32 v37, v35
	v_pk_add_f32 v[72:73], v[38:39], v[36:37]
	v_pk_add_f32 v[72:73], v[72:73], v[72:73] op_sel:[0,1] op_sel_hi:[1,0]
	v_lshl_add_u64 v[50:51], v[50:51], 0, s[20:21]
	s_waitcnt vmcnt(0)
	v_mul_f32_e32 v1, v80, v80
	v_mul_f32_e32 v61, v81, v81
	v_mov_b32_e32 v71, v1
	v_mov_b32_e32 v73, v61
	v_pk_add_f32 v[70:71], v[70:71], v[72:73]
	v_mul_f32_e32 v72, v85, v85
	v_mul_f32_e32 v74, v82, v82
	v_pk_fma_f32 v[72:73], v[84:85], v[84:85], v[72:73] op_sel_hi:[1,1,0]
	v_mul_f32_e32 v76, v83, v83
	v_mov_b32_e32 v73, v74
	v_mul_f32_e32 v74, v87, v87
	v_pk_fma_f32 v[74:75], v[86:87], v[86:87], v[74:75] op_sel_hi:[1,1,0]
	s_nop 0
	v_mov_b32_e32 v75, v76
	v_pk_add_f32 v[72:73], v[72:73], v[74:75]
	s_nop 0
	v_pk_add_f32 v[70:71], v[70:71], v[72:73]
	s_nop 0
	v_add_f32_e32 v1, v70, v71
	s_nop 1
	v_add_f32_dpp v1, v1, v1 quad_perm:[1,0,3,2] row_mask:0xf bank_mask:0xf
	s_nop 1
	v_add_f32_dpp v1, v1, v1 quad_perm:[2,3,0,1] row_mask:0xf bank_mask:0xf
	s_nop 1
	v_add_f32_dpp v1, v1, v1 row_half_mirror row_mask:0xf bank_mask:0xf
	s_nop 1
	v_add_f32_dpp v1, v1, v1 row_mirror row_mask:0xf bank_mask:0xf
	v_mov_b32_e32 v61, v1
	s_nop 1
	v_permlane16_swap_b32_e32 v1, v61
	v_add_f32_e32 v1, v1, v61
	v_mov_b32_e32 v61, v1
	s_nop 1
	v_permlane32_swap_b32_e32 v1, v61
	v_add_f32_e32 v1, v1, v61
	v_fmamk_f32 v1, v1, 0x3a800000, v201
	v_rsq_f32_e32 v70, v1
	v_add_u32_e32 v1, 0xfffffa00, v60
	v_pk_mul_f32 v[62:63], v[62:63], v[70:71] op_sel_hi:[1,0]
	v_pk_mul_f32 v[64:65], v[64:65], v[70:71] op_sel_hi:[1,0]
	v_pk_fma_f32 v[62:63], v[2:3], v[62:63], v[18:19]
	v_pk_fma_f32 v[64:65], v[4:5], v[64:65], v[20:21]
	v_cvt_pk_bf16_f32 v62, v62, v63
	v_cvt_pk_bf16_f32 v63, v64, v65
	buffer_store_dwordx2 v[62:63], v1, s[12:15], 0 offen sc1
	v_pk_mul_f32 v[62:63], v[66:67], v[70:71] op_sel_hi:[1,0]
	v_pk_mul_f32 v[64:65], v[68:69], v[70:71] op_sel_hi:[1,0]
	v_pk_fma_f32 v[62:63], v[6:7], v[62:63], v[22:23]
	v_pk_fma_f32 v[64:65], v[8:9], v[64:65], v[24:25]
	v_pk_mul_f32 v[84:85], v[84:85], v[70:71] op_sel_hi:[1,0]
	v_pk_mul_f32 v[86:87], v[86:87], v[70:71] op_sel_hi:[1,0]
	v_pk_mul_f32 v[80:81], v[80:81], v[70:71] op_sel_hi:[1,0]
	v_pk_mul_f32 v[82:83], v[82:83], v[70:71] op_sel_hi:[1,0]
	v_cvt_pk_bf16_f32 v62, v62, v63
	v_cvt_pk_bf16_f32 v63, v64, v65
	v_add_u32_e32 v1, 0xfffffc00, v60
	v_pk_fma_f32 v[86:87], v[12:13], v[86:87], v[28:29]
	v_pk_fma_f32 v[84:85], v[10:11], v[84:85], v[26:27]
	v_pk_fma_f32 v[82:83], v[16:17], v[82:83], v[32:33]
	v_pk_fma_f32 v[80:81], v[14:15], v[80:81], v[30:31]
	buffer_store_dwordx2 v[62:63], v1, s[12:15], 0 offen sc1
	v_cvt_pk_bf16_f32 v84, v84, v85
	v_cvt_pk_bf16_f32 v85, v86, v87
	v_add_u32_e32 v1, 0xfffffe00, v60
	v_cvt_pk_bf16_f32 v80, v80, v81
	v_cvt_pk_bf16_f32 v81, v82, v83
	buffer_store_dwordx2 v[84:85], v1, s[12:15], 0 offen sc1
	buffer_store_dwordx2 v[80:81], v60, s[12:15], 0 offen sc1
	v_add_u32_e32 v60, 0x800, v60
	s_cbranch_scc1 .LBB0_82

.LBB0_249:
	global_load_dwordx4 v[54:57], v[42:43], off offset:-3072
	global_load_dwordx4 v[58:61], v[42:43], off offset:-2048
	global_load_dwordx4 v[62:65], v[42:43], off
	global_load_dwordx4 v[66:69], v[42:43], off offset:-1024
	v_readlane_b32 s12, v252, 0
	s_add_i32 s0, s0, 1
	v_readlane_b32 s13, v252, 1
	v_readlane_b32 s14, v252, 2
	v_readlane_b32 s15, v252, 3
	s_cmp_ge_i32 s0, s2
	v_lshl_add_u64 v[42:43], v[42:43], 0, s[20:21]
	s_waitcnt vmcnt(0)
	v_pk_mul_f32 v[70:71], v[56:57], v[56:57]
	v_pk_mul_f32 v[72:73], v[54:55], v[54:55]
	v_pk_mul_f32 v[74:75], v[60:61], v[60:61]
	v_pk_mul_f32 v[76:77], v[58:59], v[58:59]
	v_pk_mov_b32 v[82:83], v[72:73], v[70:71] op_sel:[1,0]
	v_mov_b32_e32 v73, v71
	v_pk_mov_b32 v[70:71], v[76:77], v[74:75] op_sel:[1,0]
	v_mov_b32_e32 v77, v75
	v_mul_f32_e32 v81, v64, v64
	v_mul_f32_e32 v78, v67, v67
	v_mul_f32_e32 v80, v69, v69
	v_pk_add_f32 v[72:73], v[82:83], v[72:73]
	v_pk_add_f32 v[70:71], v[70:71], v[76:77]
	v_mul_f32_e32 v1, v62, v62
	v_mul_f32_e32 v53, v63, v63
	v_mul_f32_e32 v84, v65, v65
	v_pk_fma_f32 v[74:75], v[66:67], v[66:67], v[78:79] op_sel_hi:[1,1,0]
	v_pk_fma_f32 v[78:79], v[68:69], v[68:69], v[80:81] op_sel_hi:[1,1,0]
	v_pk_add_f32 v[72:73], v[72:73], v[72:73] op_sel:[0,1] op_sel_hi:[1,0]
	v_pk_add_f32 v[70:71], v[70:71], v[70:71] op_sel:[0,1] op_sel_hi:[1,0]
	v_mov_b32_e32 v75, v81
	v_mov_b32_e32 v79, v84
	v_mov_b32_e32 v73, v1
	v_mov_b32_e32 v71, v53
	v_pk_add_f32 v[74:75], v[74:75], v[78:79]
	v_pk_add_f32 v[70:71], v[72:73], v[70:71]
	v_add_u32_e32 v72, 0xfffffc00, v52
	v_pk_add_f32 v[70:71], v[70:71], v[74:75]
	s_nop 0
	v_add_f32_e32 v1, v70, v71
	v_add_u32_e32 v71, 0xfffffa00, v52
	s_nop 1
	v_add_f32_dpp v1, v1, v1 quad_perm:[1,0,3,2] row_mask:0xf bank_mask:0xf
	s_nop 1
	v_add_f32_dpp v1, v1, v1 quad_perm:[2,3,0,1] row_mask:0xf bank_mask:0xf
	s_nop 1
	v_add_f32_dpp v1, v1, v1 row_half_mirror row_mask:0xf bank_mask:0xf
	s_nop 1
	v_add_f32_dpp v1, v1, v1 row_mirror row_mask:0xf bank_mask:0xf
	v_mov_b32_e32 v53, v1
	s_nop 1
	v_permlane16_swap_b32_e32 v1, v53
	v_add_f32_e32 v1, v1, v53
	v_mov_b32_e32 v53, v1
	s_nop 1
	v_permlane32_swap_b32_e32 v1, v53
	v_add_f32_e32 v1, v1, v53
	v_fmamk_f32 v1, v1, 0x3a800000, v201
	v_rsq_f32_e32 v70, v1
	v_add_u32_e32 v1, 0xfffffe00, v52
	v_pk_mul_f32 v[54:55], v[54:55], v[70:71] op_sel_hi:[1,0]
	v_pk_mul_f32 v[56:57], v[56:57], v[70:71] op_sel_hi:[1,0]
	v_pk_mul_f32 v[58:59], v[58:59], v[70:71] op_sel_hi:[1,0]
	v_pk_mul_f32 v[60:61], v[60:61], v[70:71] op_sel_hi:[1,0]
	v_pk_mul_f32 v[66:67], v[66:67], v[70:71] op_sel_hi:[1,0]
	v_pk_mul_f32 v[68:69], v[68:69], v[70:71] op_sel_hi:[1,0]
	v_pk_mul_f32 v[62:63], v[62:63], v[70:71] op_sel_hi:[1,0]
	v_pk_mul_f32 v[64:65], v[64:65], v[70:71] op_sel_hi:[1,0]
	v_pk_fma_f32 v[56:57], v[4:5], v[56:57], v[28:29]
	v_pk_fma_f32 v[54:55], v[2:3], v[54:55], v[26:27]
	v_pk_fma_f32 v[60:61], v[8:9], v[60:61], v[24:25]
	v_pk_fma_f32 v[58:59], v[6:7], v[58:59], v[22:23]
	v_pk_fma_f32 v[68:69], v[12:13], v[68:69], v[20:21]
	v_pk_fma_f32 v[66:67], v[10:11], v[66:67], v[18:19]
	v_pk_fma_f32 v[64:65], v[16:17], v[64:65], v[32:33]
	v_pk_fma_f32 v[62:63], v[14:15], v[62:63], v[30:31]
	v_cvt_pk_bf16_f32 v54, v54, v55
	v_cvt_pk_bf16_f32 v55, v56, v57
	v_cvt_pk_bf16_f32 v56, v58, v59
	v_cvt_pk_bf16_f32 v57, v60, v61
	v_cvt_pk_bf16_f32 v58, v66, v67
	v_cvt_pk_bf16_f32 v59, v68, v69
	v_cvt_pk_bf16_f32 v60, v62, v63
	v_cvt_pk_bf16_f32 v61, v64, v65
	buffer_store_dwordx2 v[54:55], v71, s[12:15], 0 offen sc1
	buffer_store_dwordx2 v[56:57], v72, s[12:15], 0 offen sc1
	buffer_store_dwordx2 v[58:59], v1, s[12:15], 0 offen sc1
	buffer_store_dwordx2 v[60:61], v52, s[12:15], 0 offen sc1
	v_add_u32_e32 v52, 0x800, v52
	s_cbranch_scc1 .LBB0_252
